# E40: PH9 issues L2 warm-up loads of this tile's residual rows and row stats before the K-loop so the LayerNorm epilogue's first loads hit L2
# baseline (speedup 1.0000x reference)
.LBB0_2439:
	v_mbcnt_lo_u32_b32 v226, -1, 0
	v_mbcnt_hi_u32_b32 v226, -1, v226
	s_mul_i32 s2, s35, 48
	v_and_or_b32 v227, v226, 15, s2
	s_mul_i32 s2, s22, 0xc0
	v_add_u32_e32 v227, s2, v227
	s_lshl_b32 s2, s92, 5
	s_lshl_b32 s3, s14, 8
	s_add_i32 s2, s2, s3
	v_ashrrev_i32_e32 v228, 1, v226
	v_and_b32_e32 v228, -8, v228
	v_add_u32_e32 v228, s2, v228
	v_mov_b32_e32 v229, 0
	v_lshl_add_u64 v[228:229], v[228:229], 1, s[58:59]
	v_lshlrev_b32_e32 v230, 11, v227
	v_mov_b32_e32 v231, 0
	v_lshl_add_u64 v[228:229], v[230:231], 0, v[228:229]
	s_mov_b64 s[2:3], 0x8000
	v_lshl_add_u64 v[230:231], v[228:229], 0, s[2:3]
	s_mov_b64 s[2:3], 0x10000
	v_lshl_add_u64 v[232:233], v[228:229], 0, s[2:3]
	s_mov_b64 s[2:3], 0x30000
	v_lshl_add_u64 v[234:235], v[228:229], 0, s[2:3]
	s_mov_b64 s[2:3], 0x38000
	v_lshl_add_u64 v[236:237], v[228:229], 0, s[2:3]
	s_mov_b64 s[2:3], 0x40000
	v_lshl_add_u64 v[238:239], v[228:229], 0, s[2:3]
	v_readlane_b32 s2, v254, 25
	v_readlane_b32 s3, v254, 26
	v_lshlrev_b32_e32 v206, 3, v227
	v_mov_b32_e32 v207, 0
	v_lshl_add_u64 v[206:207], v[206:207], 0, s[2:3]
	global_load_dwordx2 v[182:183], v[206:207], off
	global_load_dwordx2 v[184:185], v[206:207], off offset:128
	global_load_dwordx2 v[186:187], v[206:207], off offset:256
	global_load_dwordx2 v[188:189], v[206:207], off offset:768
	global_load_dwordx2 v[190:191], v[206:207], off offset:896
	global_load_dwordx2 v[192:193], v[206:207], off offset:1024
	global_load_dwordx2 v[240:241], v[228:229], off
	global_load_dwordx2 v[242:243], v[230:231], off
	global_load_dwordx2 v[244:245], v[232:233], off
	global_load_dwordx2 v[246:247], v[234:235], off
	global_load_dwordx2 v[248:249], v[236:237], off
	global_load_dwordx2 v[250:251], v[238:239], off
	global_load_dwordx2 v[252:253], v[228:229], off offset:256
	global_load_dwordx2 v[210:211], v[230:231], off offset:256
	global_load_dwordx2 v[212:213], v[232:233], off offset:256
	global_load_dwordx2 v[214:215], v[234:235], off offset:256
	global_load_dwordx2 v[216:217], v[236:237], off offset:256
	global_load_dwordx2 v[218:219], v[238:239], off offset:256
	s_add_i32 s33, s33, 1
	v_readlane_b32 s4, v254, 2
	s_mul_i32 s2, s33, s95
	s_mul_hi_u32 s3, s33, s4
	s_add_i32 s3, s3, s2
	s_mul_i32 s2, s33, s4
	v_readlane_b32 s4, v254, 1
	s_add_u32 s2, s2, s4
	s_addc_u32 s3, s3, s96
	v_cmp_gt_i64_e32 vcc, s[2:3], v[124:125]
	v_cmp_lt_i64_e64 s[4:5], s[2:3], v[122:123]
	s_cbranch_vccnz .LBB0_2445
	s_ashr_i32 s3, s2, 31
	s_lshr_b32 s3, s3, 29
	s_add_i32 s8, s2, s3
	s_and_b32 s3, s8, -8
	s_sub_i32 s9, s2, s3
	s_cmp_gt_i32 s9, -1
	s_mov_b64 s[2:3], -1
	s_cbranch_scc0 .LBB0_2442
	s_lshl_b32 s10, s9, 5
	s_mov_b64 s[2:3], 0
